# combo: rs table + last-arriver barrier w/ early inv + sc1 exchange loads + no per-segment setprio + static prio older half + ret-core heavy-wave prio, baseline placement
# speedup vs baseline: 1.0008x; 1.0008x over previous
; #define PG8_STAGE(bufoff, gbase, voff) do { _Pragma("unroll") for (int _i = 0; _i < 2; ++_i) \
;         __builtin_amdgcn_global_load_lds((const unsigned*)((const char*)(gbase) + (voff)[_i]), (LAS unsigned*)(lds + (bufoff) + ldsw + _i * 8192), 16, 0, 0); } while (0)
; #define PG8_WAIT_V(n) asm volatile("s_waitcnt vmcnt(" #n ")" ::: "memory")
; #define PG8_BAR __builtin_amdgcn_s_barrier()
; template <class Epi, class Sched>
; __device__ __forceinline__ void gemm_phase(LAS unsigned char* lds, const Gemm g, const Sched& S, const Epi& E) {
;     ...
;     f32x4 acc[2][2][4][2];
; #pragma unroll
;     for (int a = 0; a < 2; ++a)
; #pragma unroll
;         for (int b = 0; b < 2; ++b)
; #pragma unroll
;             for (int m = 0; m < 4; ++m)
; #pragma unroll
;                 for (int n = 0; n < 2; ++n) acc[a][b][m][n] = (f32x4){0.f, 0.f, 0.f, 0.f};
;     ...
;     PG8_STAGE(PG8_SB(0, 0), cB, voffB); PG8_STAGE(PG8_SB(0, 1), cB + hstepB, voffB); PG8_STAGE(PG8_SA(0, 0), cA, voffA); PG8_STAGE(PG8_SA(0, 1), cA + hstepA, voffA);
;     if (wr == 1) PG8_BAR;
;     PG8_WAIT_V(2); PG8_BAR;
;     PG8_STAGE(PG8_SB(1, 0), cB + kstep, voffB); PG8_STAGE(PG8_SA(1, 0), cA + kstep, voffA); PG8_STAGE(PG8_SB(1, 1), cB + hstepB + kstep, voffB);
;     PG8_WAIT_V(6); PG8_BAR;
;     for (;;) {
.LBB0_267:
	v_lshl_add_u64 v[14:15], s[24:25], 0, v[4:5]
	v_mov_b32_e32 v3, v5
	v_and_b32_e32 v142, 15, v143
	v_and_b32_e32 v22, 48, v143
	v_lshlrev_b32_e32 v23, 2, v143
	v_lshl_add_u64 v[16:17], s[24:25], 0, v[2:3]
	s_and_b32 s48, s44, 3
	v_lshl_or_b32 v22, v142, 6, v22
	s_lshl_b32 s4, s47, 13
	v_and_b32_e32 v23, 32, v23
	s_add_i32 m0, s50, 0x18000
	v_lshl_add_u64 v[14:15], v[14:15], 0, s[36:37]
	v_lshl_add_u64 v[18:19], s[20:21], 0, v[4:5]
	v_bitop3_b32 v24, v22, s4, v23 bitop3:0xde
	s_lshl_b32 s4, s48, 12
	s_waitcnt vmcnt(2)
	s_barrier
	global_load_lds_dwordx4 v[14:15], off
	v_lshl_add_u64 v[14:15], v[16:17], 0, s[36:37]
	s_add_i32 m0, s50, 0x1a000
	s_add_i32 s54, s50, 0x8000
	s_add_i32 s55, s50, 0xa000
	v_lshl_add_u64 v[20:21], s[20:21], 0, v[2:3]
	v_bitop3_b32 v144, v22, s4, v23 bitop3:0xde
	global_load_lds_dwordx4 v[14:15], off
	v_lshl_add_u64 v[14:15], v[18:19], 0, s[36:37]
	s_mov_b32 m0, s54
	s_add_u32 s4, s24, 0x158080
	global_load_lds_dwordx4 v[14:15], off
	v_lshl_add_u64 v[14:15], v[20:21], 0, s[36:37]
	s_mov_b32 m0, s55
	s_addc_u32 s5, s25, 0
	global_load_lds_dwordx4 v[14:15], off
	s_add_i32 m0, s50, 0x1c000
	v_lshl_add_u64 v[14:15], s[4:5], 0, v[4:5]
	global_load_lds_dwordx4 v[14:15], off
	v_lshl_add_u64 v[14:15], s[4:5], 0, v[2:3]
	s_add_i32 m0, s50, 0x1e000
	s_movk_i32 s10, 0x1580
	global_load_lds_dwordx4 v[14:15], off
	v_lshrrev_b32_e32 v11, 1, v11
	v_mul_lo_u32 v10, v10, s10
	s_mov_b32 s22, 0x15800
	v_mad_u64_u32 v[10:11], s[4:5], v11, s22, v[10:11]
	v_or_b32_e32 v10, v10, v12
	v_add_lshl_u32 v134, v10, v13, 1
	v_lshrrev_b32_e32 v10, 1, v6
	v_mul_lo_u32 v6, v7, s10
	v_mad_u64_u32 v[6:7], s[4:5], v10, s22, v[6:7]
	s_waitcnt vmcnt(6)
	v_or_b32_e32 v6, v6, v8
	s_cmpk_lt_u32 s45, 0x100
	v_add_lshl_u32 v136, v6, v9, 1
	v_mov_b32_e32 v6, 0
	v_readlane_b32 s4, v254, 13
	s_cselect_b64 s[18:19], -1, 0
	v_mov_b32_e32 v135, v5
	v_mov_b32_e32 v137, v5
	s_mov_b32 s59, 0
	v_add_u32_e32 v145, 0, v24
	s_mov_b32 s10, s4
	v_readlane_b32 s46, v253, 61
	v_mov_b32_e32 v7, v6
	v_mov_b32_e32 v8, v6
	v_mov_b32_e32 v9, v6
	v_mov_b32_e32 v10, v6
	v_mov_b32_e32 v11, v6
	v_mov_b32_e32 v12, v6
	v_mov_b32_e32 v13, v6
	v_mov_b32_e32 v14, v6
	v_mov_b32_e32 v15, v6
	v_mov_b32_e32 v16, v6
	v_mov_b32_e32 v17, v6
	v_mov_b32_e32 v18, v6
	v_mov_b32_e32 v19, v6
	v_mov_b32_e32 v20, v6
	v_mov_b32_e32 v21, v6
	v_mov_b32_e32 v22, v6
	v_mov_b32_e32 v23, v6
	v_mov_b32_e32 v24, v6
	v_mov_b32_e32 v25, v6
	v_mov_b32_e32 v30, v6
	v_mov_b32_e32 v31, v6
	v_mov_b32_e32 v32, v6
	v_mov_b32_e32 v33, v6
	v_mov_b32_e32 v38, v6
	v_mov_b32_e32 v39, v6
	v_mov_b32_e32 v40, v6
	v_mov_b32_e32 v41, v6
	v_mov_b32_e32 v46, v6
	v_mov_b32_e32 v47, v6
	v_mov_b32_e32 v48, v6
	v_mov_b32_e32 v49, v6
	v_mov_b32_e32 v26, v6
	v_mov_b32_e32 v27, v6
	v_mov_b32_e32 v28, v6
	v_mov_b32_e32 v29, v6
	v_mov_b32_e32 v34, v6
	v_mov_b32_e32 v35, v6
	v_mov_b32_e32 v36, v6
	v_mov_b32_e32 v37, v6
	v_mov_b32_e32 v42, v6
	v_mov_b32_e32 v43, v6
	v_mov_b32_e32 v44, v6
	v_mov_b32_e32 v45, v6
	v_mov_b32_e32 v50, v6
	v_mov_b32_e32 v51, v6
	v_mov_b32_e32 v52, v6
	v_mov_b32_e32 v53, v6
	v_mov_b32_e32 v54, v6
	v_mov_b32_e32 v55, v6
	v_mov_b32_e32 v56, v6
	v_mov_b32_e32 v57, v6
	v_mov_b32_e32 v58, v6
	v_mov_b32_e32 v59, v6
	v_mov_b32_e32 v60, v6
	v_mov_b32_e32 v61, v6
	v_mov_b32_e32 v62, v6
	v_mov_b32_e32 v63, v6
	v_mov_b32_e32 v64, v6
	v_mov_b32_e32 v65, v6
	v_mov_b32_e32 v66, v6
	v_mov_b32_e32 v67, v6
	v_mov_b32_e32 v68, v6
	v_mov_b32_e32 v69, v6
	v_mov_b32_e32 v70, v6
	v_mov_b32_e32 v71, v6
	v_mov_b32_e32 v72, v6
	v_mov_b32_e32 v73, v6
	v_mov_b32_e32 v74, v6
	v_mov_b32_e32 v75, v6
	v_mov_b32_e32 v76, v6
	v_mov_b32_e32 v77, v6
	v_mov_b32_e32 v78, v6
	v_mov_b32_e32 v79, v6
	v_mov_b32_e32 v80, v6
	v_mov_b32_e32 v81, v6
	v_mov_b32_e32 v82, v6
	v_mov_b32_e32 v83, v6
	v_mov_b32_e32 v84, v6
	v_mov_b32_e32 v85, v6
	v_mov_b32_e32 v86, v6
	v_mov_b32_e32 v87, v6
	v_mov_b32_e32 v88, v6
	v_mov_b32_e32 v89, v6
	v_mov_b32_e32 v94, v6
	v_mov_b32_e32 v95, v6
	v_mov_b32_e32 v96, v6
	v_mov_b32_e32 v97, v6
	v_mov_b32_e32 v102, v6
	v_mov_b32_e32 v103, v6
	v_mov_b32_e32 v104, v6
	v_mov_b32_e32 v105, v6
	v_mov_b32_e32 v114, v6
	v_mov_b32_e32 v115, v6
	v_mov_b32_e32 v116, v6
	v_mov_b32_e32 v117, v6
	v_mov_b32_e32 v90, v6
	v_mov_b32_e32 v91, v6
	v_mov_b32_e32 v92, v6
	v_mov_b32_e32 v93, v6
	v_mov_b32_e32 v98, v6
	v_mov_b32_e32 v99, v6
	v_mov_b32_e32 v100, v6
	v_mov_b32_e32 v101, v6
	v_mov_b32_e32 v106, v6
	v_mov_b32_e32 v107, v6
	v_mov_b32_e32 v108, v6
	v_mov_b32_e32 v109, v6
	v_mov_b32_e32 v110, v6
	v_mov_b32_e32 v111, v6
	v_mov_b32_e32 v112, v6
	v_mov_b32_e32 v113, v6
	v_mov_b32_e32 v118, v6
	v_mov_b32_e32 v119, v6
	v_mov_b32_e32 v120, v6
	v_mov_b32_e32 v121, v6
	v_mov_b32_e32 v122, v6
	v_mov_b32_e32 v123, v6
	v_mov_b32_e32 v124, v6
	v_mov_b32_e32 v125, v6
	v_mov_b32_e32 v126, v6
	v_mov_b32_e32 v127, v6
	v_mov_b32_e32 v128, v6
	v_mov_b32_e32 v129, v6
	v_mov_b32_e32 v130, v6
	v_mov_b32_e32 v131, v6
	v_mov_b32_e32 v132, v6
	v_mov_b32_e32 v133, v6
	s_barrier
	s_branch .LBB0_270
	s_nop 0
	s_nop 0
	s_nop 0
	s_nop 0
	s_nop 0
	s_nop 0
	s_nop 0
	s_nop 0
	s_nop 0
	s_nop 0
	s_nop 0
	s_nop 0
	s_nop 0
	s_nop 0
	s_nop 0
	s_nop 0
	s_nop 0
	s_nop 0
	s_nop 0
	s_nop 0
	s_nop 0
	s_nop 0
	s_nop 0
	s_nop 0
	s_nop 0
	s_nop 0
	s_nop 0
	s_nop 0
	s_nop 0
	s_nop 0
	s_nop 0
	s_nop 0
	s_nop 0
	s_nop 0
	s_nop 0
	s_nop 0
	s_nop 0
	s_nop 0
.LBB0_268:
	s_mov_b64 s[22:23], s[24:25]
	s_mov_b64 s[4:5], s[20:21]
	s_mov_b32 s58, s59
	s_andn2_b64 vcc, exec, s[38:39]
	s_cbranch_vccz .LBB0_288

; #define PG8_STAGE(bufoff, gbase, voff) do { _Pragma("unroll") for (int _i = 0; _i < 2; ++_i) \
;         __builtin_amdgcn_global_load_lds((const unsigned*)((const char*)(gbase) + (voff)[_i]), (LAS unsigned*)(lds + (bufoff) + ldsw + _i * 8192), 16, 0, 0); } while (0)
; #define PG8_WAIT_V(n) asm volatile("s_waitcnt vmcnt(" #n ")" ::: "memory")
; #define PG8_BAR __builtin_amdgcn_s_barrier()
;     __device__ __forceinline__ void operator()(const f32x4 (&acc)[2][2][4][2], const Unit& u, int wr, int wc, int fr, int fq) const {
;         const int row0 = u.pm * BM + wr * 64 + fr, j0 = 8 * fq, cbase = u.pn * BM + 64 * wc;
;         const f32x4 ba0 = *(const f32x4*)(bias + cbase + j0), ba1 = *(const f32x4*)(bias + cbase + j0 + 4), bb0 = *(const f32x4*)(bias + cbase + 32 + j0), bb1 = *(const f32x4*)(bias + cbase + 32 + j0 + 4);
;         const bool rot = u.pn < 9;
;         f32x4 TB[2][6];
; template <class Epi, class Sched>
; __device__ __forceinline__ void gemm_phase(LAS unsigned char* lds, const Gemm g, const Sched& S, const Epi& E) {
;     ...
;     PG8_WAIT_V(2); PG8_BAR;
;     PG8_STAGE(PG8_SB(1, 0), cB + kstep, voffB); PG8_STAGE(PG8_SA(1, 0), cA + kstep, voffA); PG8_STAGE(PG8_SB(1, 1), cB + hstepB + kstep, voffB);
;     PG8_WAIT_V(6); PG8_BAR;
.LBB0_507:
	v_lshrrev_b32_e32 v20, 1, v4
	v_and_b32_e32 v20, 24, v20
	v_and_b32_e32 v21, 15, v4
	v_lshlrev_b32_e32 v22, 1, v20
	v_lshlrev_b32_e32 v4, 2, v4
	s_and_b32 s20, s17, 3
	v_lshl_or_b32 v235, s18, 6, v21
	v_lshl_or_b32 v21, v21, 6, v22
	s_lshl_b32 s17, s18, 13
	v_and_b32_e32 v4, 32, v4
	s_add_i32 m0, s50, 0x18000
	v_lshl_add_u64 v[12:13], v[12:13], 0, s[36:37]
	v_bitop3_b32 v22, v21, s17, v4 bitop3:0xde
	s_lshl_b32 s17, s20, 12
	s_waitcnt vmcnt(2)
	s_barrier
	global_load_lds_dwordx4 v[12:13], off
	v_lshl_add_u64 v[10:11], v[10:11], 0, s[36:37]
	s_add_i32 m0, s50, 0x1a000
	s_add_i32 s54, s50, 0x8000
	s_add_i32 s55, s50, 0xa000
	global_load_lds_dwordx4 v[10:11], off
	v_lshl_add_u64 v[6:7], v[6:7], 0, s[36:37]
	s_mov_b32 m0, s54
	s_add_u32 s18, s42, 0x80080
	global_load_lds_dwordx4 v[6:7], off
	v_lshl_add_u64 v[6:7], v[8:9], 0, s[36:37]
	s_mov_b32 m0, s55
	s_addc_u32 s19, s43, 0
	global_load_lds_dwordx4 v[6:7], off
	s_add_i32 m0, s50, 0x1c000
	v_lshl_add_u64 v[6:7], s[18:19], 0, v[212:213]
	global_load_lds_dwordx4 v[6:7], off
	v_lshl_add_u64 v[6:7], s[18:19], 0, v[216:217]
	s_add_i32 m0, s50, 0x1e000
	v_bitop3_b32 v236, v21, s17, v4 bitop3:0xde
	global_load_lds_dwordx4 v[6:7], off
	v_lshlrev_b32_e32 v4, 2, v20
	v_lshl_add_u64 v[218:219], s[12:13], 0, v[4:5]
	v_lshl_add_u64 v[220:221], s[10:11], 0, v[4:5]
	v_lshl_add_u64 v[222:223], s[14:15], 0, v[4:5]
	v_lshlrev_b32_e32 v4, 15, v14
	v_and_b32_e32 v4, 0xffff0000, v4
	v_lshl_add_u32 v4, v15, 12, v4
	v_and_b32_e32 v6, 1, v14
	v_lshl_or_b32 v4, v6, 6, v4
	v_lshl_add_u32 v224, v16, 1, v4
	v_lshlrev_b32_e32 v4, 15, v17
	v_and_b32_e32 v4, 0xffff0000, v4
	s_waitcnt vmcnt(6)
	v_lshl_add_u32 v4, v18, 12, v4
	v_and_b32_e32 v6, 1, v17
	s_cmpk_lt_u32 s16, 0x100
	v_lshl_or_b32 v4, v6, 6, v4
	s_cselect_b64 s[16:17], -1, 0
	s_lshl_b32 s56, s20, 6
	v_mov_b32_e32 v225, v5
	v_lshl_add_u32 v226, v19, 1, v4
	v_mov_b32_e32 v227, v5
	s_mov_b32 s57, 0
	v_add_u32_e32 v237, 0, v22
	v_lshlrev_b32_e32 v4, 1, v20
	s_barrier
	s_branch .LBB0_510
	s_nop 0
	s_nop 0
	s_nop 0
	s_nop 0
	s_nop 0
	s_nop 0
	s_nop 0
	s_nop 0
	s_nop 0
	s_nop 0
	s_nop 0
.LBB0_508:
	s_mov_b64 s[26:27], 0

; __device__ __forceinline__ float log2_gamma(int hd) { const float e = ldexpf(1.0f, -5 - hd); float p = 1.0f / 7.0f; p = p * e + 1.0f / 6.0f; p = p * e + 0.2f; p = p * e + 0.25f; p = p * e + 1.0f / 3.0f; p = p * e + 0.5f; p = p * e + 1.0f; return -1.44269504089f * e * p; }
; #define PG8_STAGE(bufoff, gbase, voff) do { _Pragma("unroll") for (int _i = 0; _i < 2; ++_i) \
;         __builtin_amdgcn_global_load_lds((const unsigned*)((const char*)(gbase) + (voff)[_i]), (LAS unsigned*)(lds + (bufoff) + ldsw + _i * 8192), 16, 0, 0); } while (0)
; #define PG8_WAIT_V(n) asm volatile("s_waitcnt vmcnt(" #n ")" ::: "memory")
; #define PG8_BAR __builtin_amdgcn_s_barrier()
;     __device__ __forceinline__ void operator()(const f32x4 (&acc)[2][2][4][2], const Unit& u, int wr, int wc, int fr, int fq) const {
;         const int row0 = u.pm * BM + wr * 64 + fr, j0 = wc * 32 + 8 * fq;
;         if (u.pn < 16) {
;             const int hd = u.pn & 7; const bool isq = u.pn < 8;
;             const float l2g = log2_gamma(hd);
;             f32x4 TB[2][6];
; template <class Epi, class Sched>
; __device__ __forceinline__ void gemm_phase(LAS unsigned char* lds, const Gemm g, const Sched& S, const Epi& E) {
;     ...
;     PG8_STAGE(PG8_SB(0, 0), cB, voffB); PG8_STAGE(PG8_SB(0, 1), cB + hstepB, voffB); PG8_STAGE(PG8_SA(0, 0), cA, voffA); PG8_STAGE(PG8_SA(0, 1), cA + hstepA, voffA);
;     if (wr == 1) PG8_BAR;
;     PG8_WAIT_V(2); PG8_BAR;
;     PG8_STAGE(PG8_SB(1, 0), cB + kstep, voffB); PG8_STAGE(PG8_SA(1, 0), cA + kstep, voffA); PG8_STAGE(PG8_SB(1, 1), cB + hstepB + kstep, voffB);
;     PG8_WAIT_V(6); PG8_BAR;
.LBB0_649:
	s_add_u32 s8, s14, 0xd000000
	v_lshrrev_b32_e32 v20, 1, v4
	s_addc_u32 s9, s15, 0
	v_and_b32_e32 v189, 15, v4
	v_and_b32_e32 v21, 24, v20
	s_add_u32 s10, s14, 0x100000
	v_lshlrev_b32_e32 v20, 1, v21
	v_lshlrev_b32_e32 v22, 6, v189
	v_lshlrev_b32_e32 v4, 2, v4
	s_addc_u32 s11, s15, 0
	s_and_b32 s18, s13, 3
	v_or_b32_e32 v23, v22, v20
	s_lshl_b32 s13, s16, 13
	v_and_b32_e32 v4, 32, v4
	s_add_i32 m0, s47, 0x18000
	v_lshl_add_u64 v[12:13], v[12:13], 0, s[36:37]
	s_lshl_b32 s51, s16, 6
	v_bitop3_b32 v24, v23, s13, v4 bitop3:0xde
	s_lshl_b32 s13, s18, 12
	s_waitcnt vmcnt(2)
	s_barrier
	global_load_lds_dwordx4 v[12:13], off
	v_lshl_add_u64 v[10:11], v[10:11], 0, s[36:37]
	s_add_i32 m0, s47, 0x1a000
	s_add_i32 s52, s47, 0x8000
	s_add_i32 s53, s47, 0xa000
	global_load_lds_dwordx4 v[10:11], off
	v_lshl_add_u64 v[6:7], v[6:7], 0, s[36:37]
	s_mov_b32 m0, s52
	s_add_u32 s16, s28, 0x80080
	global_load_lds_dwordx4 v[6:7], off
	v_lshl_add_u64 v[6:7], v[8:9], 0, s[36:37]
	s_mov_b32 m0, s53
	s_addc_u32 s17, s29, 0
	global_load_lds_dwordx4 v[6:7], off
	s_add_i32 m0, s47, 0x1c000
	v_lshl_add_u64 v[6:7], s[16:17], 0, v[182:183]
	global_load_lds_dwordx4 v[6:7], off
	v_lshl_add_u64 v[6:7], s[16:17], 0, v[186:187]
	s_add_i32 m0, s47, 0x1e000
	v_lshl_or_b32 v188, s18, 5, v21
	global_load_lds_dwordx4 v[6:7], off
	v_bitop3_b32 v231, v23, s13, v4 bitop3:0xde
	v_lshlrev_b32_e32 v4, 2, v188
	v_lshl_add_u64 v[6:7], s[14:15], 0, v[4:5]
	s_mov_b64 s[16:17], 0x200000
	s_cmpk_lt_u32 s12, 0x100
	v_lshl_add_u64 v[190:191], v[6:7], 0, s[16:17]
	s_mov_b64 s[16:17], 0x600000
	s_cselect_b64 s[12:13], -1, 0
	v_lshl_add_u64 v[192:193], v[6:7], 0, s[16:17]
	s_lshl_b32 s16, s18, 10
	s_add_u32 s14, s14, s16
	s_addc_u32 s15, s15, 0
	v_mov_b32_e32 v23, v5
	v_lshl_add_u64 v[6:7], s[14:15], 0, v[22:23]
	v_mov_b32_e32 v21, v5
	v_lshlrev_b32_e32 v4, 15, v14
	v_lshl_add_u64 v[6:7], v[6:7], 0, v[20:21]
	s_mov_b64 s[14:15], 0x5000000
	v_and_b32_e32 v4, 0xffff0000, v4
	v_lshl_add_u64 v[194:195], v[6:7], 0, s[14:15]
	v_lshl_add_u32 v4, v15, 12, v4
	v_and_b32_e32 v6, 1, v14
	v_lshl_or_b32 v4, v6, 6, v4
	v_lshl_add_u32 v196, v16, 1, v4
	v_lshlrev_b32_e32 v4, 15, v17
	v_and_b32_e32 v4, 0xffff0000, v4
	s_waitcnt vmcnt(6)
	v_lshl_add_u32 v4, v18, 12, v4
	v_and_b32_e32 v6, 1, v17
	v_lshl_or_b32 v4, v6, 6, v4
	v_mov_b32_e32 v197, v5
	v_lshl_add_u32 v212, v19, 1, v4
	v_mov_b32_e32 v213, v5
	s_mov_b32 s54, 0
	v_add_u32_e32 v235, 0, v24
	s_barrier
	s_branch .LBB0_652
	s_nop 0
	s_nop 0
	s_nop 0
	s_nop 0
.LBB0_650:
	s_mov_b64 s[22:23], 0

; #define PG8_STAGE(bufoff, gbase, voff) do { _Pragma("unroll") for (int _i = 0; _i < 2; ++_i) \
;         __builtin_amdgcn_global_load_lds((const unsigned*)((const char*)(gbase) + (voff)[_i]), (LAS unsigned*)(lds + (bufoff) + ldsw + _i * 8192), 16, 0, 0); } while (0)
; #define PG8_WAIT_V(n) asm volatile("s_waitcnt vmcnt(" #n ")" ::: "memory")
; #define PG8_BAR __builtin_amdgcn_s_barrier()
; template <class Epi, class Sched>
; __device__ __forceinline__ void gemm_phase(LAS unsigned char* lds, const Gemm g, const Sched& S, const Epi& E) {
;     ...
;     f32x4 acc[2][2][4][2];
; #pragma unroll
;     for (int a = 0; a < 2; ++a)
; #pragma unroll
;         for (int b = 0; b < 2; ++b)
; #pragma unroll
;             for (int m = 0; m < 4; ++m)
; #pragma unroll
;                 for (int n = 0; n < 2; ++n) acc[a][b][m][n] = (f32x4){0.f, 0.f, 0.f, 0.f};
;     bf16x8 At[4][2], B0[2][2], B1[2][2];
;     const char* cA = (const char*)g.A + (size_t)cur.pm * tstepA + (size_t)cur.ka * 2; const char* cB = (const char*)g.Bt + (size_t)cur.pn * tstepB;
;     S.a_ready(cur);
;     PG8_STAGE(PG8_SB(0, 0), cB, voffB); PG8_STAGE(PG8_SB(0, 1), cB + hstepB, voffB); PG8_STAGE(PG8_SA(0, 0), cA, voffA); PG8_STAGE(PG8_SA(0, 1), cA + hstepA, voffA);
;     if (wr == 1) PG8_BAR;
;     PG8_WAIT_V(2); PG8_BAR;
;     PG8_STAGE(PG8_SB(1, 0), cB + kstep, voffB); PG8_STAGE(PG8_SA(1, 0), cA + kstep, voffA); PG8_STAGE(PG8_SB(1, 1), cB + hstepB + kstep, voffB);
;     PG8_WAIT_V(6); PG8_BAR;
.LBB0_995:
	v_mov_b32_e32 v139, v5
	v_lshl_add_u64 v[10:11], s[24:25], 0, v[138:139]
	v_mov_b32_e32 v135, v5
	v_lshl_add_u64 v[12:13], s[24:25], 0, v[134:135]
	v_mov_b32_e32 v141, v5
	s_add_i32 m0, s58, 0x18000
	v_lshl_add_u64 v[10:11], v[10:11], 0, s[36:37]
	v_lshl_add_u64 v[18:19], s[26:27], 0, v[140:141]
	v_mov_b32_e32 v137, v5
	s_waitcnt vmcnt(2)
	s_barrier
	global_load_lds_dwordx4 v[10:11], off
	v_lshl_add_u64 v[10:11], v[12:13], 0, s[36:37]
	s_add_i32 m0, s58, 0x1a000
	s_add_i32 s62, s58, 0x8000
	v_lshl_add_u64 v[20:21], s[26:27], 0, v[136:137]
	global_load_lds_dwordx4 v[10:11], off
	v_lshl_add_u64 v[10:11], v[18:19], 0, s[36:37]
	s_mov_b32 m0, s62
	s_add_i32 s63, s58, 0xa000
	v_lshl_add_u64 v[14:15], s[4:5], 0, v[138:139]
	global_load_lds_dwordx4 v[10:11], off
	v_lshl_add_u64 v[10:11], v[20:21], 0, s[36:37]
	s_mov_b32 m0, s63
	v_lshl_add_u64 v[16:17], s[4:5], 0, v[134:135]
	global_load_lds_dwordx4 v[10:11], off
	s_add_i32 m0, s58, 0x1c000
	v_lshl_add_u64 v[10:11], v[14:15], 0, s[36:37]
	global_load_lds_dwordx4 v[10:11], off
	v_lshl_add_u64 v[10:11], v[16:17], 0, s[36:37]
	s_add_i32 m0, s58, 0x1e000
	v_and_b32_e32 v168, 15, v169
	global_load_lds_dwordx4 v[10:11], off
	v_and_b32_e32 v9, 48, v169
	v_lshlrev_b32_e32 v10, 2, v169
	s_and_b32 s54, s50, 3
	s_lshr_b32 s64, s6, 6
	v_lshl_or_b32 v9, v168, 6, v9
	s_lshl_b32 s4, s52, 13
	v_and_b32_e32 v10, 32, v10
	v_bitop3_b32 v11, v9, s4, v10 bitop3:0xde
	s_lshl_b32 s4, s54, 12
	s_add_i32 s65, s64, -2
	s_cmpk_lt_u32 s51, 0x100
	v_bitop3_b32 v148, v9, s4, v10 bitop3:0xde
	s_cselect_b64 s[28:29], -1, 0
	s_add_u32 s4, s34, 0x80
	v_add_u32_e32 v4, v8, v4
	s_addc_u32 s5, 0, 0
	v_add_lshl_u32 v4, v4, v7, 1
	v_add_u32_e32 v2, v6, v2
	v_lshl_add_u64 v[142:143], s[4:5], 0, v[4:5]
	v_add_lshl_u32 v4, v2, v3, 1
	s_waitcnt vmcnt(6)
	v_lshl_add_u64 v[144:145], s[4:5], 0, v[4:5]
	v_mov_b32_e32 v4, v5
	v_mov_b32_e32 v2, v5
	v_mov_b32_e32 v3, v5
	v_add_u32_e32 v149, 0, v11
	v_mov_b64_e32 v[8:9], v[4:5]
	v_mov_b64_e32 v[12:13], v[4:5]
	v_mov_b64_e32 v[16:17], v[4:5]
	v_mov_b64_e32 v[20:21], v[4:5]
	v_mov_b64_e32 v[24:25], v[4:5]
	v_mov_b64_e32 v[32:33], v[4:5]
	v_mov_b64_e32 v[40:41], v[4:5]
	v_mov_b64_e32 v[48:49], v[4:5]
	v_mov_b64_e32 v[28:29], v[4:5]
	v_mov_b64_e32 v[36:37], v[4:5]
	v_mov_b64_e32 v[44:45], v[4:5]
	v_mov_b64_e32 v[52:53], v[4:5]
	v_mov_b64_e32 v[56:57], v[4:5]
	v_mov_b64_e32 v[60:61], v[4:5]
	v_mov_b64_e32 v[64:65], v[4:5]
	v_mov_b64_e32 v[68:69], v[4:5]
	v_mov_b64_e32 v[72:73], v[4:5]
	v_mov_b64_e32 v[76:77], v[4:5]
	v_mov_b64_e32 v[80:81], v[4:5]
	v_mov_b64_e32 v[84:85], v[4:5]
	v_mov_b64_e32 v[88:89], v[4:5]
	v_mov_b64_e32 v[96:97], v[4:5]
	v_mov_b64_e32 v[104:105], v[4:5]
	v_mov_b64_e32 v[116:117], v[4:5]
	v_mov_b64_e32 v[92:93], v[4:5]
	v_mov_b64_e32 v[100:101], v[4:5]
	v_mov_b64_e32 v[108:109], v[4:5]
	v_mov_b64_e32 v[112:113], v[4:5]
	v_mov_b64_e32 v[120:121], v[4:5]
	v_mov_b64_e32 v[124:125], v[4:5]
	v_mov_b64_e32 v[128:129], v[4:5]
	v_mov_b64_e32 v[132:133], v[4:5]
	v_readlane_b32 s4, v254, 13
	s_mov_b32 s66, 0
	v_mov_b64_e32 v[6:7], v[2:3]
	v_mov_b64_e32 v[10:11], v[2:3]
	v_mov_b64_e32 v[14:15], v[2:3]
	v_mov_b64_e32 v[18:19], v[2:3]
	v_mov_b64_e32 v[22:23], v[2:3]
	v_mov_b64_e32 v[30:31], v[2:3]
	v_mov_b64_e32 v[38:39], v[2:3]
	v_mov_b64_e32 v[46:47], v[2:3]
	v_mov_b64_e32 v[26:27], v[2:3]
	v_mov_b64_e32 v[34:35], v[2:3]
	v_mov_b64_e32 v[42:43], v[2:3]
	v_mov_b64_e32 v[50:51], v[2:3]
	v_mov_b64_e32 v[54:55], v[2:3]
	v_mov_b64_e32 v[58:59], v[2:3]
	v_mov_b64_e32 v[62:63], v[2:3]
	v_mov_b64_e32 v[66:67], v[2:3]
	v_mov_b64_e32 v[70:71], v[2:3]
	v_mov_b64_e32 v[74:75], v[2:3]
	v_mov_b64_e32 v[78:79], v[2:3]
	v_mov_b64_e32 v[82:83], v[2:3]
	v_mov_b64_e32 v[86:87], v[2:3]
	v_mov_b64_e32 v[94:95], v[2:3]
	v_mov_b64_e32 v[102:103], v[2:3]
	v_mov_b64_e32 v[114:115], v[2:3]
	v_mov_b64_e32 v[90:91], v[2:3]
	v_mov_b64_e32 v[98:99], v[2:3]
	v_mov_b64_e32 v[106:107], v[2:3]
	v_mov_b64_e32 v[110:111], v[2:3]
	v_mov_b64_e32 v[118:119], v[2:3]
	v_mov_b64_e32 v[122:123], v[2:3]
	v_mov_b64_e32 v[126:127], v[2:3]
	v_mov_b64_e32 v[130:131], v[2:3]
	s_mov_b32 s6, s4
	v_readlane_b32 s53, v253, 61
	s_barrier
	s_branch .LBB0_998
	s_nop 0
	s_nop 0
	s_nop 0
	s_nop 0
	s_nop 0
	s_nop 0
	s_nop 0
	s_nop 0
	s_nop 0
	s_nop 0
	s_nop 0
	s_nop 0
	s_nop 0
	s_nop 0
	s_nop 0
	s_nop 0
	s_nop 0
	s_nop 0
	s_nop 0
	s_nop 0
	s_nop 0
	s_nop 0
	s_nop 0
	s_nop 0
	s_nop 0
	s_nop 0
	s_nop 0
	s_nop 0
	s_nop 0
	s_nop 0
	s_nop 0
	s_nop 0
	s_nop 0
	s_nop 0
	s_nop 0
	s_nop 0
	s_nop 0
	s_nop 0
	s_nop 0
	s_nop 0
	s_nop 0
	s_nop 0
	s_nop 0
	s_nop 0
	s_nop 0
	s_nop 0
	s_nop 0
	s_nop 0
	s_nop 0
	s_nop 0
	s_nop 0
	s_nop 0
	s_nop 0
	s_nop 0
	s_nop 0
